# S5 scan item: wave-specialised half-chunk pipeline (wave0 recurrence, wave1 u staging + B*u, waves 2-3 C*h+gelu+store), one barrier per 32 tokens
# speedup vs baseline: 1.0013x; 1.0013x over previous
.LBB0_437:
	s_or_b64 exec, exec, s[16:17]
	v_mul_f32_e32 v0, 0x3fb8aa3b, v16
	v_fma_f32 v2, v16, s86, -v0
	v_rndne_f32_e32 v3, v0
	v_fmac_f32_e32 v2, 0x32a5705f, v16
	v_sub_f32_e32 v0, v0, v3
	v_add_f32_e32 v0, v0, v2
	v_cvt_i32_f32_e32 v2, v3
	v_exp_f32_e32 v0, v0
	v_xor_b32_e32 v66, v52, v66
	s_lshl_b32 s16, s36, 5
	s_and_b32 s16, s16, 0x3e0
	v_ldexp_f32 v0, v0, v2
	v_mul_f32_e32 v2, v67, v67
	v_fmamk_f32 v3, v2, 0xb94c1982, v195
	v_fmaak_f32 v3, v2, v3, 0xbe2aaa9d
	v_mul_f32_e32 v3, v2, v3
	v_fmac_f32_e32 v67, v67, v3
	v_fmamk_f32 v3, v2, 0x37d75334, v196
	v_fmaak_f32 v3, v2, v3, 0x3d2aabf7
	v_fmaak_f32 v3, v2, v3, 0xbf000004
	v_fma_f32 v2, v2, v3, 1.0
	v_lshlrev_b32_e32 v3, 30, v68
	v_and_b32_e32 v68, 1, v68
	v_cndmask_b32_e32 v0, 0, v0, vcc
	v_cmp_eq_u32_e32 vcc, 0, v68
	v_and_b32_e32 v16, 0x80000000, v3
	v_cndmask_b32_e64 v0, v207, v0, s[0:1]
	v_cndmask_b32_e32 v68, v2, v67, vcc
	v_xor_b32_e32 v66, v66, v68
	v_xor_b32_e32 v16, v66, v16
	v_xor_b32_e32 v66, 0x80000000, v67
	v_cndmask_b32_e32 v2, v66, v2, vcc
	s_mul_i32 s0, s14, 0xa00000
	v_bitop3_b32 v2, v2, v3, s58 bitop3:0x78
	v_cmp_lg_f32_e32 vcc, s37, v52
	s_mul_hi_i32 s1, s14, 0xa00000
	s_or_b32 s0, s0, s16
	v_cndmask_b32_e32 v2, v209, v2, vcc
	v_cndmask_b32_e32 v3, v209, v16, vcc
	v_cvt_pk_bf16_f32 v25, v25, -v29
	v_cvt_pk_bf16_f32 v24, v24, -v28
	s_waitcnt vmcnt(3)
	v_cvt_pk_bf16_f32 v29, v41, -v45
	v_cvt_pk_bf16_f32 v28, v40, -v44
	v_lshl_add_u64 v[40:41], v[94:95], 0, s[0:1]
	s_lshl_b64 s[0:1], s[14:15], 21
	v_mul_f32_e32 v2, v0, v2
	v_mul_f32_e32 v52, v0, v3
	s_or_b32 s0, s0, s16
	v_mov_b32_e32 v0, v1
	v_cvt_pk_bf16_f32 v19, v65, v19
	v_cvt_pk_bf16_f32 v18, v64, v18
	v_cvt_pk_bf16_f32 v17, v63, v17
	v_cvt_pk_bf16_f32 v16, v62, v61
	v_cvt_pk_bf16_f32 v23, v23, -v51
	v_cvt_pk_bf16_f32 v22, v22, -v50
	v_cvt_pk_bf16_f32 v21, v21, -v49
	v_cvt_pk_bf16_f32 v20, v20, -v48
	v_cvt_pk_bf16_f32 v27, v27, -v31
	v_cvt_pk_bf16_f32 v26, v26, -v30
	v_cvt_pk_bf16_f32 v31, v43, -v47
	v_cvt_pk_bf16_f32 v30, v42, -v46
	s_waitcnt vmcnt(1)
	v_cvt_pk_bf16_f32 v35, v35, -v39
	v_cvt_pk_bf16_f32 v34, v34, -v38
	v_cvt_pk_bf16_f32 v33, v33, -v37
	v_cvt_pk_bf16_f32 v32, v32, -v36
	v_cvt_pk_bf16_f32 v39, v60, v59
	v_cvt_pk_bf16_f32 v38, v58, v57
	v_cvt_pk_bf16_f32 v37, v56, v55
	v_cvt_pk_bf16_f32 v36, v54, v53
	v_mov_b32_e32 v3, v2
	v_mov_b32_e32 v53, v52
	v_lshl_add_u64 v[42:43], v[108:109], 0, s[0:1]
	s_mov_b64 s[0:1], 0
	v_mov_b64_e32 v[44:45], v[0:1]
	s_waitcnt vmcnt(0)
	v_readfirstlane_b32 s99, v162
	v_and_b32_e32 v0, 63, v162
	v_lshlrev_b32_e32 v0, 4, v0
	v_lshrrev_b32_e32 v50, 6, v162
	v_lshl_add_u32 v50, v50, 11, v0
	s_lshr_b32 s99, s99, 6
	ds_write_b128 v50, v[36:39] offset:32768
	ds_write_b128 v50, v[16:19] offset:33792
	v_mov_b32_e32 v46, 0
	v_mov_b32_e32 v47, 0
	v_mov_b32_e32 v48, 0
	v_mov_b32_e32 v49, 0
	v_lshlrev_b32_e32 v51, 4, v162
	ds_write_b128 v51, v[46:49] offset:55296
	v_lshlrev_b32_e32 v51, 2, v162
	ds_write_b32 v51, v46 offset:59392
	s_and_saveexec_b64 s[14:15], s[6:7]
	ds_write_b128 v187, v[12:15] offset:50176
	s_or_b64 exec, exec, s[14:15]
	v_xor_b32_e32 v253, 0x80, v97
	v_xor_b32_e32 v254, 0x100, v97
	v_xor_b32_e32 v255, 0x180, v97
	v_xor_b32_e32 v214, 0x80, v204
	v_mov_b32_e32 v216, v204
	v_xor_b32_e32 v217, 0x180, v204
	v_xor_b32_e32 v218, 0x100, v204
	v_add_u32_e32 v231, 0xffffde00, v205
	v_add_u32_e32 v53, 0xfffff600, v206
	v_add_u32_e32 v230, 0xfffff600, v187
	s_mov_b32 s0, 0xffff8000
	s_mov_b32 s1, -1
	v_lshl_add_u64 v[42:43], v[42:43], 0, s[0:1]
	s_mov_b32 s0, 0xfffd8000
	v_lshl_add_u64 v[248:249], v[40:41], 0, s[0:1]
	s_mov_b64 s[0:1], 0x28000
	s_cmp_lg_u32 s99, 1
	s_cbranch_scc1 .Ls5p_pre
	global_load_dwordx4 v[12:15], v[248:249], off
	v_lshl_add_u64 v[248:249], v[248:249], 0, s[0:1]
	global_load_dwordx4 v[210:213], v[248:249], off
	v_lshl_add_u64 v[248:249], v[248:249], 0, s[0:1]
.Ls5p_pre:
	s_waitcnt lgkmcnt(0)
	s_barrier
	ds_read_b128 v[168:171], v0 offset:32768
	ds_read_b128 v[172:175], v0 offset:33792
	ds_read_b128 v[176:179], v0 offset:34816
	ds_read_b128 v[180:183], v0 offset:35840
	ds_read_b128 v[126:129], v0 offset:36864
	ds_read_b128 v[130:133], v0 offset:37888
	ds_read_b128 v[220:223], v0 offset:38912
	ds_read_b128 v[224:227], v0 offset:39936
	ds_read_b128 v[46:49], v203 offset:50176
	ds_read_b128 v[54:57], v203 offset:51456
	v_add_u32_e32 v0, 0x400, v204
	ds_read_b128 v[66:69], v203 offset:52736
	ds_read_b128 v[122:125], v203 offset:54016
	v_add_u32_e32 v50, 0x2000, v204
	s_waitcnt lgkmcnt(3)
	v_mfma_f32_16x16x32_bf16 v[58:61], v[46:49], v[36:39], 0
	v_mfma_f32_16x16x32_bf16 v[46:49], v[46:49], v[16:19], 0
	s_nop 7
	ds_write2_b32 v204, v58, v46 offset1:16
	ds_write2_b32 v204, v59, v47 offset0:128 offset1:144
	ds_write2_b32 v0, v60, v48 offset1:16
	ds_write2_b32 v0, v61, v49 offset0:128 offset1:144
	s_waitcnt lgkmcnt(6)
	v_mfma_f32_16x16x32_bf16 v[62:65], v[54:57], v[36:39], 0
	v_add_u32_e32 v0, 0x2400, v204
	v_mfma_f32_16x16x32_bf16 v[46:49], v[54:57], v[16:19], 0
	s_nop 7
	ds_write2_b32 v50, v62, v46 offset1:16
	ds_write2_b32 v50, v63, v47 offset0:128 offset1:144
	s_waitcnt lgkmcnt(7)
	v_mfma_f32_16x16x32_bf16 v[54:57], v[66:69], v[36:39], 0
	ds_write2_b32 v0, v64, v48 offset1:16
	ds_write2_b32 v0, v65, v49 offset0:128 offset1:144
	v_add_u32_e32 v0, 0x4000, v204
	v_mfma_f32_16x16x32_bf16 v[46:49], v[66:69], v[16:19], 0
	s_nop 7
	ds_write2_b32 v0, v54, v46 offset1:16
	ds_write2_b32 v0, v55, v47 offset0:128 offset1:144
	v_add_u32_e32 v0, 0x4400, v204
	s_waitcnt lgkmcnt(10)
	v_mfma_f32_16x16x32_bf16 v[58:61], v[122:125], v[36:39], 0
	ds_write2_b32 v0, v56, v48 offset1:16
	ds_write2_b32 v0, v57, v49 offset0:128 offset1:144
	v_add_u32_e32 v0, 0x6000, v204
	v_mfma_f32_16x16x32_bf16 v[46:49], v[122:125], v[16:19], 0
	s_nop 7
	ds_write2_b32 v0, v58, v46 offset1:16
	ds_write2_b32 v0, v59, v47 offset0:128 offset1:144
	v_add_u32_e32 v0, 0x6400, v204
	ds_write2_b32 v0, v60, v48 offset1:16
	ds_write2_b32 v0, v61, v49 offset0:128 offset1:144
	s_waitcnt lgkmcnt(0)
	s_barrier
	s_mov_b32 s98, 0
.Ls5p_loop:
	s_cmp_eq_u32 s99, 0
	s_cbranch_scc1 .Ls5p_scan0
	s_cmp_eq_u32 s99, 1
	s_cbranch_scc1 .Ls5p_bu0
	s_cmp_eq_u32 s98, 0
	s_cbranch_scc1 .Ls5p_sync0
	ds_read_b128 v[46:49], v231 offset:41472
	ds_read_b128 v[54:57], v231 offset:41536
	s_waitcnt lgkmcnt(1)
	v_mfma_f32_16x16x32_bf16 v[46:49], v[20:23], v[46:49], 0
	ds_read_b64 v[50:51], v53 offset:57856
	s_waitcnt lgkmcnt(1)
	v_mfma_f32_16x16x32_bf16 v[46:49], v[24:27], v[54:57], v[46:49]
	ds_read_b128 v[54:57], v231 offset:41600
	s_waitcnt lgkmcnt(0)
	v_mfma_f32_16x16x32_bf16 v[46:49], v[28:31], v[54:57], v[46:49]
	ds_read_b128 v[54:57], v231 offset:41664
	s_waitcnt lgkmcnt(0)
	v_mfma_f32_16x16x32_bf16 v[46:49], v[32:35], v[54:57], v[46:49]
	v_lshlrev_b32_e32 v54, 16, v50
	v_and_b32_e32 v55, 0xffff0000, v50
	s_nop 0
	s_nop 4
	v_pk_fma_f32 v[46:47], v[8:9], v[54:55], v[46:47]
	s_nop 0
	v_mul_f32_e32 v0, 0x3d372713, v46
	v_mul_f32_e32 v0, v46, v0
	v_fma_f32 v0, v46, v0, v46
	v_mul_f32_e32 v0, 0x3f4c422a, v0
	v_add_f32_e32 v0, v0, v0
	v_mul_f32_e32 v0, 0x3fb8aa3b, v0
	v_exp_f32_e32 v54, v0
	v_mul_f32_e32 v0, 0x3d372713, v47
	v_mul_f32_e32 v0, v47, v0
	v_fma_f32 v0, v47, v0, v47
	v_mul_f32_e32 v0, 0x3f4c422a, v0
	v_add_f32_e32 v0, v0, v0
	v_mul_f32_e32 v0, 0x3fb8aa3b, v0
	v_exp_f32_e32 v55, v0
	v_pk_mul_f32 v[46:47], v[46:47], 0.5 op_sel_hi:[1,0]
	v_pk_add_f32 v[54:55], v[54:55], 1.0 op_sel_hi:[1,0]
	s_nop 0
	v_div_scale_f32 v0, s[14:15], v55, v55, 2.0
	v_rcp_f32_e32 v50, v0
	s_nop 0
	v_fma_f32 v56, -v0, v50, 1.0
	v_fmac_f32_e32 v50, v56, v50
	v_div_scale_f32 v56, vcc, 2.0, v55, 2.0
	v_mul_f32_e32 v57, v56, v50
	v_fma_f32 v58, -v0, v57, v56
	v_fmac_f32_e32 v57, v58, v50
	v_fma_f32 v0, -v0, v57, v56
	v_div_fmas_f32 v0, v0, v50, v57
	v_div_fixup_f32 v55, v0, v55, 2.0
	v_div_scale_f32 v0, s[14:15], v54, v54, 2.0
	v_rcp_f32_e32 v50, v0
	s_nop 0
	v_fma_f32 v56, -v0, v50, 1.0
	v_fmac_f32_e32 v50, v56, v50
	v_div_scale_f32 v56, vcc, 2.0, v54, 2.0
	v_mul_f32_e32 v57, v56, v50
	v_fma_f32 v58, -v0, v57, v56
	v_fmac_f32_e32 v57, v58, v50
	v_fma_f32 v0, -v0, v57, v56
	v_div_fmas_f32 v0, v0, v50, v57
	v_lshlrev_b32_e32 v50, 16, v51
	v_and_b32_e32 v51, 0xffff0000, v51
	v_pk_fma_f32 v[48:49], v[10:11], v[50:51], v[48:49]
	v_div_fixup_f32 v54, v0, v54, 2.0
	v_mul_f32_e32 v0, 0x3d372713, v48
	v_mul_f32_e32 v0, v48, v0
	v_fma_f32 v0, v48, v0, v48
	v_mul_f32_e32 v0, 0x3f4c422a, v0
	v_add_f32_e32 v0, v0, v0
	v_mul_f32_e32 v0, 0x3fb8aa3b, v0
	v_exp_f32_e32 v50, v0
	v_mul_f32_e32 v0, 0x3d372713, v49
	v_mul_f32_e32 v0, v49, v0
	v_fma_f32 v0, v49, v0, v49
	v_mul_f32_e32 v0, 0x3f4c422a, v0
	v_add_f32_e32 v0, v0, v0
	v_mul_f32_e32 v0, 0x3fb8aa3b, v0
	v_exp_f32_e32 v51, v0
	v_pk_add_f32 v[54:55], v[54:55], 1.0 op_sel_hi:[1,0] neg_lo:[1,0] neg_hi:[1,0]
	v_pk_mul_f32 v[48:49], v[48:49], 0.5 op_sel_hi:[1,0]
	v_pk_add_f32 v[54:55], v[54:55], 1.0 op_sel_hi:[1,0]
	v_pk_add_f32 v[50:51], v[50:51], 1.0 op_sel_hi:[1,0]
	v_pk_mul_f32 v[46:47], v[46:47], v[54:55]
	v_div_scale_f32 v0, s[14:15], v51, v51, 2.0
	v_rcp_f32_e32 v54, v0
	v_cvt_pk_bf16_f32 v46, v46, v47
	v_fma_f32 v55, -v0, v54, 1.0
	v_fmac_f32_e32 v54, v55, v54
	v_div_scale_f32 v55, vcc, 2.0, v51, 2.0
	v_mul_f32_e32 v56, v55, v54
	v_fma_f32 v57, -v0, v56, v55
	v_fmac_f32_e32 v56, v57, v54
	v_fma_f32 v0, -v0, v56, v55
	v_div_fmas_f32 v0, v0, v54, v56
	v_div_fixup_f32 v51, v0, v51, 2.0
	v_div_scale_f32 v0, s[14:15], v50, v50, 2.0
	v_rcp_f32_e32 v54, v0
	s_mov_b64 s[14:15], 0x8000
	v_fma_f32 v55, -v0, v54, 1.0
	v_fmac_f32_e32 v54, v55, v54
	v_div_scale_f32 v55, vcc, 2.0, v50, 2.0
	v_mul_f32_e32 v56, v55, v54
	v_fma_f32 v57, -v0, v56, v55
	v_fmac_f32_e32 v56, v57, v54
	v_fma_f32 v0, -v0, v56, v55
	v_div_fmas_f32 v0, v0, v54, v56
	v_div_fixup_f32 v50, v0, v50, 2.0
	v_pk_add_f32 v[50:51], v[50:51], 1.0 op_sel_hi:[1,0] neg_lo:[1,0] neg_hi:[1,0]
	s_nop 0
	v_pk_add_f32 v[50:51], v[50:51], 1.0 op_sel_hi:[1,0]
	s_nop 0
	v_pk_mul_f32 v[48:49], v[48:49], v[50:51]
	s_nop 0
	v_cvt_pk_bf16_f32 v47, v48, v49
	global_store_dwordx2 v[42:43], v[46:47], off offset:-4
	v_lshl_add_u64 v[42:43], v[42:43], 0, s[14:15]
	s_branch .Ls5p_sync0
.Ls5p_scan0:
	ds_read_b64 v[232:233], v97
	ds_read_b64 v[234:235], v97 offset:512
	ds_read_b64 v[236:237], v97 offset:1024
	ds_read_b64 v[238:239], v97 offset:1536
	ds_read_b64 v[240:241], v253 offset:2048
	ds_read_b64 v[242:243], v253 offset:2560
	ds_read_b64 v[244:245], v253 offset:3072
	ds_read_b64 v[246:247], v253 offset:3584
	ds_read_b64 v[54:55], v254 offset:4096
	ds_read_b64 v[56:57], v254 offset:4608
	ds_read_b64 v[58:59], v254 offset:5120
	ds_read_b64 v[60:61], v254 offset:5632
	ds_read_b64 v[62:63], v255 offset:6144
	ds_read_b64 v[64:65], v255 offset:6656
	ds_read_b64 v[46:47], v255 offset:7168
	s_waitcnt lgkmcnt(8)
	ds_read_b64 v[48:49], v255 offset:7680
	ds_read_b64 v[168:169], v97 offset:8192
	ds_read_b64 v[170:171], v97 offset:8704
	ds_read_b64 v[172:173], v97 offset:9216
	ds_read_b64 v[174:175], v97 offset:9728
	ds_read_b64 v[176:177], v253 offset:10240
	ds_read_b64 v[178:179], v253 offset:10752
	s_waitcnt lgkmcnt(8)
	ds_read_b64 v[180:181], v253 offset:11264
	ds_read_b64 v[182:183], v253 offset:11776
	ds_read_b64 v[126:127], v254 offset:12288
	ds_read_b64 v[128:129], v254 offset:12800
	ds_read_b64 v[130:131], v254 offset:13312
	ds_read_b64 v[132:133], v254 offset:13824
	ds_read_b64 v[220:221], v255 offset:14336
	s_waitcnt lgkmcnt(8)
	ds_read_b64 v[222:223], v255 offset:14848
	ds_read_b64 v[224:225], v255 offset:15360
	ds_read_b64 v[226:227], v255 offset:15872
	v_fma_f32 v50, -v52, v45, v232
	v_fma_f32 v51, v52, v44, v233
	v_fma_f32 v44, v2, v44, v50
	v_fma_f32 v45, v2, v45, v51
	v_cvt_pk_bf16_f32 v0, v44, v45
	ds_write_b32 v229, v0 offset:32768
	v_fma_f32 v50, -v52, v45, v234
	v_fma_f32 v51, v52, v44, v235
	v_fma_f32 v44, v2, v44, v50
	v_fma_f32 v45, v2, v45, v51
	v_cvt_pk_bf16_f32 v66, v44, v45
	ds_write_b32 v229, v66 offset:33040
	v_fma_f32 v50, -v52, v45, v236
	v_fma_f32 v51, v52, v44, v237
	v_fma_f32 v44, v2, v44, v50
	v_fma_f32 v45, v2, v45, v51
	v_cvt_pk_bf16_f32 v0, v44, v45
	ds_write_b32 v229, v0 offset:33312
	v_fma_f32 v50, -v52, v45, v238
	v_fma_f32 v51, v52, v44, v239
	v_fma_f32 v44, v2, v44, v50
	v_fma_f32 v45, v2, v45, v51
	v_cvt_pk_bf16_f32 v66, v44, v45
	ds_write_b32 v229, v66 offset:33584
	v_fma_f32 v50, -v52, v45, v240
	v_fma_f32 v51, v52, v44, v241
	v_fma_f32 v44, v2, v44, v50
	v_fma_f32 v45, v2, v45, v51
	v_cvt_pk_bf16_f32 v0, v44, v45
	s_waitcnt lgkmcnt(8)
	ds_write_b32 v229, v0 offset:33856
	v_fma_f32 v50, -v52, v45, v242
	v_fma_f32 v51, v52, v44, v243
	v_fma_f32 v44, v2, v44, v50
	v_fma_f32 v45, v2, v45, v51
	v_cvt_pk_bf16_f32 v66, v44, v45
	ds_write_b32 v229, v66 offset:34128
	v_fma_f32 v50, -v52, v45, v244
	v_fma_f32 v51, v52, v44, v245
	v_fma_f32 v44, v2, v44, v50
	v_fma_f32 v45, v2, v45, v51
	v_cvt_pk_bf16_f32 v0, v44, v45
	ds_write_b32 v229, v0 offset:34400
	v_fma_f32 v50, -v52, v45, v246
	v_fma_f32 v51, v52, v44, v247
	v_fma_f32 v44, v2, v44, v50
	v_fma_f32 v45, v2, v45, v51
	v_cvt_pk_bf16_f32 v66, v44, v45
	ds_write_b32 v229, v66 offset:34672
	v_fma_f32 v50, -v52, v45, v54
	v_fma_f32 v51, v52, v44, v55
	v_fma_f32 v44, v2, v44, v50
	v_fma_f32 v45, v2, v45, v51
	v_cvt_pk_bf16_f32 v0, v44, v45
	ds_write_b32 v229, v0 offset:34944
	v_fma_f32 v50, -v52, v45, v56
	v_fma_f32 v51, v52, v44, v57
	v_fma_f32 v44, v2, v44, v50
	v_fma_f32 v45, v2, v45, v51
	v_cvt_pk_bf16_f32 v66, v44, v45
	ds_write_b32 v229, v66 offset:35216
	v_fma_f32 v50, -v52, v45, v58
	v_fma_f32 v51, v52, v44, v59
	v_fma_f32 v44, v2, v44, v50
	v_fma_f32 v45, v2, v45, v51
	v_cvt_pk_bf16_f32 v0, v44, v45
	ds_write_b32 v229, v0 offset:35488
	v_fma_f32 v50, -v52, v45, v60
	v_fma_f32 v51, v52, v44, v61
	v_fma_f32 v44, v2, v44, v50
	v_fma_f32 v45, v2, v45, v51
	v_cvt_pk_bf16_f32 v66, v44, v45
	s_waitcnt lgkmcnt(8)
	ds_write_b32 v229, v66 offset:35760
	v_fma_f32 v50, -v52, v45, v62
	v_fma_f32 v51, v52, v44, v63
	v_fma_f32 v44, v2, v44, v50
	v_fma_f32 v45, v2, v45, v51
	v_cvt_pk_bf16_f32 v0, v44, v45
	ds_write_b32 v229, v0 offset:36032
	v_fma_f32 v50, -v52, v45, v64
	v_fma_f32 v51, v52, v44, v65
	v_fma_f32 v44, v2, v44, v50
	v_fma_f32 v45, v2, v45, v51
	v_cvt_pk_bf16_f32 v66, v44, v45
	ds_write_b32 v229, v66 offset:36304
	v_fma_f32 v50, -v52, v45, v46
	v_fma_f32 v51, v52, v44, v47
	v_fma_f32 v44, v2, v44, v50
	v_fma_f32 v45, v2, v45, v51
	v_cvt_pk_bf16_f32 v0, v44, v45
	ds_write_b32 v229, v0 offset:36576
	v_fma_f32 v50, -v52, v45, v48
	v_fma_f32 v51, v52, v44, v49
	v_fma_f32 v44, v2, v44, v50
	v_fma_f32 v45, v2, v45, v51
	v_cvt_pk_bf16_f32 v66, v44, v45
	ds_write_b32 v229, v66 offset:36848
	v_fma_f32 v50, -v52, v45, v168
	v_fma_f32 v51, v52, v44, v169
	v_fma_f32 v44, v2, v44, v50
	v_fma_f32 v45, v2, v45, v51
	v_cvt_pk_bf16_f32 v0, v44, v45
	ds_write_b32 v229, v0 offset:37120
	v_fma_f32 v50, -v52, v45, v170
	v_fma_f32 v51, v52, v44, v171
	v_fma_f32 v44, v2, v44, v50
	v_fma_f32 v45, v2, v45, v51
	v_cvt_pk_bf16_f32 v66, v44, v45
	ds_write_b32 v229, v66 offset:37392
	v_fma_f32 v50, -v52, v45, v172
	v_fma_f32 v51, v52, v44, v173
	v_fma_f32 v44, v2, v44, v50
	v_fma_f32 v45, v2, v45, v51
	v_cvt_pk_bf16_f32 v0, v44, v45
	s_waitcnt lgkmcnt(8)
	ds_write_b32 v229, v0 offset:37664
	v_fma_f32 v50, -v52, v45, v174
	v_fma_f32 v51, v52, v44, v175
	v_fma_f32 v44, v2, v44, v50
	v_fma_f32 v45, v2, v45, v51
	v_cvt_pk_bf16_f32 v66, v44, v45
	ds_write_b32 v229, v66 offset:37936
	v_fma_f32 v50, -v52, v45, v176
	v_fma_f32 v51, v52, v44, v177
	v_fma_f32 v44, v2, v44, v50
	v_fma_f32 v45, v2, v45, v51
	v_cvt_pk_bf16_f32 v0, v44, v45
	ds_write_b32 v229, v0 offset:38208
	v_fma_f32 v50, -v52, v45, v178
	v_fma_f32 v51, v52, v44, v179
	v_fma_f32 v44, v2, v44, v50
	v_fma_f32 v45, v2, v45, v51
	v_cvt_pk_bf16_f32 v66, v44, v45
	ds_write_b32 v229, v66 offset:38480
	v_fma_f32 v50, -v52, v45, v180
	v_fma_f32 v51, v52, v44, v181
	v_fma_f32 v44, v2, v44, v50
	v_fma_f32 v45, v2, v45, v51
	v_cvt_pk_bf16_f32 v0, v44, v45
	ds_write_b32 v229, v0 offset:38752
	v_fma_f32 v50, -v52, v45, v182
	v_fma_f32 v51, v52, v44, v183
	v_fma_f32 v44, v2, v44, v50
	v_fma_f32 v45, v2, v45, v51
	v_cvt_pk_bf16_f32 v66, v44, v45
	ds_write_b32 v229, v66 offset:39024
	v_fma_f32 v50, -v52, v45, v126
	v_fma_f32 v51, v52, v44, v127
	v_fma_f32 v44, v2, v44, v50
	v_fma_f32 v45, v2, v45, v51
	v_cvt_pk_bf16_f32 v0, v44, v45
	ds_write_b32 v229, v0 offset:39296
	v_fma_f32 v50, -v52, v45, v128
	v_fma_f32 v51, v52, v44, v129
	v_fma_f32 v44, v2, v44, v50
	v_fma_f32 v45, v2, v45, v51
	v_cvt_pk_bf16_f32 v66, v44, v45
	s_waitcnt lgkmcnt(8)
	ds_write_b32 v229, v66 offset:39568
	v_fma_f32 v50, -v52, v45, v130
	v_fma_f32 v51, v52, v44, v131
	v_fma_f32 v44, v2, v44, v50
	v_fma_f32 v45, v2, v45, v51
	v_cvt_pk_bf16_f32 v0, v44, v45
	ds_write_b32 v229, v0 offset:39840
	v_fma_f32 v50, -v52, v45, v132
	v_fma_f32 v51, v52, v44, v133
	v_fma_f32 v44, v2, v44, v50
	v_fma_f32 v45, v2, v45, v51
	v_cvt_pk_bf16_f32 v66, v44, v45
	ds_write_b32 v229, v66 offset:40112
	v_fma_f32 v50, -v52, v45, v220
	v_fma_f32 v51, v52, v44, v221
	v_fma_f32 v44, v2, v44, v50
	v_fma_f32 v45, v2, v45, v51
	v_cvt_pk_bf16_f32 v0, v44, v45
	ds_write_b32 v229, v0 offset:40384
	v_fma_f32 v50, -v52, v45, v222
	v_fma_f32 v51, v52, v44, v223
	v_fma_f32 v44, v2, v44, v50
	v_fma_f32 v45, v2, v45, v51
	v_cvt_pk_bf16_f32 v66, v44, v45
	ds_write_b32 v229, v66 offset:40656
	v_fma_f32 v50, -v52, v45, v224
	v_fma_f32 v51, v52, v44, v225
	v_fma_f32 v44, v2, v44, v50
	v_fma_f32 v45, v2, v45, v51
	v_cvt_pk_bf16_f32 v0, v44, v45
	ds_write_b32 v229, v0 offset:40928
	v_fma_f32 v50, -v52, v45, v226
	v_fma_f32 v51, v52, v44, v227
	v_fma_f32 v44, v2, v44, v50
	v_fma_f32 v45, v2, v45, v51
	v_cvt_pk_bf16_f32 v66, v44, v45
	ds_write_b32 v229, v66 offset:41200
	s_branch .Ls5p_sync0
.Ls5p_bu0:
	s_cmp_lt_u32 s98, 15
	s_cbranch_scc0 .Ls5p_last0
	s_waitcnt vmcnt(1)
	ds_write_b128 v230, v[12:15] offset:55296
	global_load_dwordx4 v[12:15], v[248:249], off
	v_lshl_add_u64 v[248:249], v[248:249], 0, s[0:1]
	s_branch .Ls5p_cont0
.Ls5p_last0:
	s_waitcnt vmcnt(0)
	ds_write_b128 v230, v[12:15] offset:55296
.Ls5p_cont0:
	ds_read_b128 v[46:49], v203 offset:52736
	ds_read_b128 v[54:57], v203 offset:54016
	s_waitcnt lgkmcnt(1)
	v_mfma_f32_16x16x32_bf16 v[58:61], v[46:49], v[168:171], 0
	v_mfma_f32_16x16x32_bf16 v[62:65], v[46:49], v[172:175], 0
	v_add_u32_e32 v0, 0x4000, v214
	v_add_u32_e32 v50, 0x4400, v214
	v_mfma_f32_16x16x32_bf16 v[122:125], v[46:49], v[176:179], 0
	v_mfma_f32_16x16x32_bf16 v[198:201], v[46:49], v[180:183], 0
	v_add_u32_e32 v51, 0x4000, v216
	v_add_u32_e32 v66, 0x4400, v216
	v_mfma_f32_16x16x32_bf16 v[232:235], v[46:49], v[126:129], 0
	v_mfma_f32_16x16x32_bf16 v[236:239], v[46:49], v[130:133], 0
	v_add_u32_e32 v253, 0x4000, v217
	v_add_u32_e32 v254, 0x4400, v217
	v_mfma_f32_16x16x32_bf16 v[240:243], v[46:49], v[220:223], 0
	v_mfma_f32_16x16x32_bf16 v[244:247], v[46:49], v[224:227], 0
	v_add_u32_e32 v255, 0x4000, v218
	v_add_u32_e32 v113, 0x4400, v218
	s_nop 3
	ds_write2_b32 v0, v58, v62 offset1:16
	ds_write2_b32 v0, v59, v63 offset0:128 offset1:144
	ds_write2_b32 v50, v60, v64 offset1:16
	ds_write2_b32 v50, v61, v65 offset0:128 offset1:144
	ds_write2_b32 v51, v122, v198 offset1:16
	ds_write2_b32 v51, v123, v199 offset0:128 offset1:144
	ds_write2_b32 v66, v124, v200 offset1:16
	ds_write2_b32 v66, v125, v201 offset0:128 offset1:144
	ds_write2_b32 v253, v232, v236 offset1:16
	ds_write2_b32 v253, v233, v237 offset0:128 offset1:144
	ds_write2_b32 v254, v234, v238 offset1:16
	ds_write2_b32 v254, v235, v239 offset0:128 offset1:144
	ds_write2_b32 v255, v240, v244 offset1:16
	ds_write2_b32 v255, v241, v245 offset0:128 offset1:144
	ds_write2_b32 v113, v242, v246 offset1:16
	ds_write2_b32 v113, v243, v247 offset0:128 offset1:144
	s_waitcnt lgkmcnt(0)
	v_mfma_f32_16x16x32_bf16 v[58:61], v[54:57], v[168:171], 0
	v_mfma_f32_16x16x32_bf16 v[62:65], v[54:57], v[172:175], 0
	v_add_u32_e32 v0, 0x6000, v214
	v_add_u32_e32 v50, 0x6400, v214
	v_mfma_f32_16x16x32_bf16 v[122:125], v[54:57], v[176:179], 0
	v_mfma_f32_16x16x32_bf16 v[198:201], v[54:57], v[180:183], 0
	v_add_u32_e32 v51, 0x6000, v216
	v_add_u32_e32 v66, 0x6400, v216
	v_mfma_f32_16x16x32_bf16 v[232:235], v[54:57], v[126:129], 0
	v_mfma_f32_16x16x32_bf16 v[236:239], v[54:57], v[130:133], 0
	v_add_u32_e32 v253, 0x6000, v217
	v_add_u32_e32 v254, 0x6400, v217
	v_mfma_f32_16x16x32_bf16 v[240:243], v[54:57], v[220:223], 0
	v_mfma_f32_16x16x32_bf16 v[244:247], v[54:57], v[224:227], 0
	v_add_u32_e32 v255, 0x6000, v218
	v_add_u32_e32 v113, 0x6400, v218
	s_nop 3
	ds_write2_b32 v0, v58, v62 offset1:16
	ds_write2_b32 v0, v59, v63 offset0:128 offset1:144
	ds_write2_b32 v50, v60, v64 offset1:16
	ds_write2_b32 v50, v61, v65 offset0:128 offset1:144
	ds_write2_b32 v51, v122, v198 offset1:16
	ds_write2_b32 v51, v123, v199 offset0:128 offset1:144
	ds_write2_b32 v66, v124, v200 offset1:16
	ds_write2_b32 v66, v125, v201 offset0:128 offset1:144
	ds_write2_b32 v253, v232, v236 offset1:16
	ds_write2_b32 v253, v233, v237 offset0:128 offset1:144
	ds_write2_b32 v254, v234, v238 offset1:16
	ds_write2_b32 v254, v235, v239 offset0:128 offset1:144
	ds_write2_b32 v255, v240, v244 offset1:16
	ds_write2_b32 v255, v241, v245 offset0:128 offset1:144
	ds_write2_b32 v113, v242, v246 offset1:16
	ds_write2_b32 v113, v243, v247 offset0:128 offset1:144
.Ls5p_sync0:
	s_waitcnt lgkmcnt(0)
	s_barrier
	s_cmp_eq_u32 s99, 0
	s_cbranch_scc1 .Ls5p_scan1
	s_cmp_eq_u32 s99, 1
	s_cbranch_scc1 .Ls5p_bu1
	ds_read_b128 v[46:49], v231 offset:32768
	ds_read_b128 v[54:57], v231 offset:32832
	s_waitcnt lgkmcnt(1)
	v_mfma_f32_16x16x32_bf16 v[46:49], v[20:23], v[46:49], 0
	ds_read_b64 v[50:51], v53 offset:50176
	s_waitcnt lgkmcnt(1)
	v_mfma_f32_16x16x32_bf16 v[46:49], v[24:27], v[54:57], v[46:49]
	ds_read_b128 v[54:57], v231 offset:32896
	s_waitcnt lgkmcnt(0)
	v_mfma_f32_16x16x32_bf16 v[46:49], v[28:31], v[54:57], v[46:49]
	ds_read_b128 v[54:57], v231 offset:32960
	s_waitcnt lgkmcnt(0)
	v_mfma_f32_16x16x32_bf16 v[46:49], v[32:35], v[54:57], v[46:49]
	v_lshlrev_b32_e32 v54, 16, v50
	v_and_b32_e32 v55, 0xffff0000, v50
	s_nop 0
	s_nop 4
	v_pk_fma_f32 v[46:47], v[8:9], v[54:55], v[46:47]
	s_nop 0
	v_mul_f32_e32 v0, 0x3d372713, v46
	v_mul_f32_e32 v0, v46, v0
	v_fma_f32 v0, v46, v0, v46
	v_mul_f32_e32 v0, 0x3f4c422a, v0
	v_add_f32_e32 v0, v0, v0
	v_mul_f32_e32 v0, 0x3fb8aa3b, v0
	v_exp_f32_e32 v54, v0
	v_mul_f32_e32 v0, 0x3d372713, v47
	v_mul_f32_e32 v0, v47, v0
	v_fma_f32 v0, v47, v0, v47
	v_mul_f32_e32 v0, 0x3f4c422a, v0
	v_add_f32_e32 v0, v0, v0
	v_mul_f32_e32 v0, 0x3fb8aa3b, v0
	v_exp_f32_e32 v55, v0
	v_pk_mul_f32 v[46:47], v[46:47], 0.5 op_sel_hi:[1,0]
	v_pk_add_f32 v[54:55], v[54:55], 1.0 op_sel_hi:[1,0]
	s_nop 0
	v_div_scale_f32 v0, s[14:15], v55, v55, 2.0
	v_rcp_f32_e32 v50, v0
	s_nop 0
	v_fma_f32 v56, -v0, v50, 1.0
	v_fmac_f32_e32 v50, v56, v50
	v_div_scale_f32 v56, vcc, 2.0, v55, 2.0
	v_mul_f32_e32 v57, v56, v50
	v_fma_f32 v58, -v0, v57, v56
	v_fmac_f32_e32 v57, v58, v50
	v_fma_f32 v0, -v0, v57, v56
	v_div_fmas_f32 v0, v0, v50, v57
	v_div_fixup_f32 v55, v0, v55, 2.0
	v_div_scale_f32 v0, s[14:15], v54, v54, 2.0
	v_rcp_f32_e32 v50, v0
	s_nop 0
	v_fma_f32 v56, -v0, v50, 1.0
	v_fmac_f32_e32 v50, v56, v50
	v_div_scale_f32 v56, vcc, 2.0, v54, 2.0
	v_mul_f32_e32 v57, v56, v50
	v_fma_f32 v58, -v0, v57, v56
	v_fmac_f32_e32 v57, v58, v50
	v_fma_f32 v0, -v0, v57, v56
	v_div_fmas_f32 v0, v0, v50, v57
	v_lshlrev_b32_e32 v50, 16, v51
	v_and_b32_e32 v51, 0xffff0000, v51
	v_pk_fma_f32 v[48:49], v[10:11], v[50:51], v[48:49]
	v_div_fixup_f32 v54, v0, v54, 2.0
	v_mul_f32_e32 v0, 0x3d372713, v48
	v_mul_f32_e32 v0, v48, v0
	v_fma_f32 v0, v48, v0, v48
	v_mul_f32_e32 v0, 0x3f4c422a, v0
	v_add_f32_e32 v0, v0, v0
	v_mul_f32_e32 v0, 0x3fb8aa3b, v0
	v_exp_f32_e32 v50, v0
	v_mul_f32_e32 v0, 0x3d372713, v49
	v_mul_f32_e32 v0, v49, v0
	v_fma_f32 v0, v49, v0, v49
	v_mul_f32_e32 v0, 0x3f4c422a, v0
	v_add_f32_e32 v0, v0, v0
	v_mul_f32_e32 v0, 0x3fb8aa3b, v0
	v_exp_f32_e32 v51, v0
	v_pk_add_f32 v[54:55], v[54:55], 1.0 op_sel_hi:[1,0] neg_lo:[1,0] neg_hi:[1,0]
	v_pk_mul_f32 v[48:49], v[48:49], 0.5 op_sel_hi:[1,0]
	v_pk_add_f32 v[54:55], v[54:55], 1.0 op_sel_hi:[1,0]
	v_pk_add_f32 v[50:51], v[50:51], 1.0 op_sel_hi:[1,0]
	v_pk_mul_f32 v[46:47], v[46:47], v[54:55]
	v_div_scale_f32 v0, s[14:15], v51, v51, 2.0
	v_rcp_f32_e32 v54, v0
	v_cvt_pk_bf16_f32 v46, v46, v47
	v_fma_f32 v55, -v0, v54, 1.0
	v_fmac_f32_e32 v54, v55, v54
	v_div_scale_f32 v55, vcc, 2.0, v51, 2.0
	v_mul_f32_e32 v56, v55, v54
	v_fma_f32 v57, -v0, v56, v55
	v_fmac_f32_e32 v56, v57, v54
	v_fma_f32 v0, -v0, v56, v55
	v_div_fmas_f32 v0, v0, v54, v56
	v_div_fixup_f32 v51, v0, v51, 2.0
	v_div_scale_f32 v0, s[14:15], v50, v50, 2.0
	v_rcp_f32_e32 v54, v0
	s_mov_b64 s[14:15], 0x8000
	v_fma_f32 v55, -v0, v54, 1.0
	v_fmac_f32_e32 v54, v55, v54
	v_div_scale_f32 v55, vcc, 2.0, v50, 2.0
	v_mul_f32_e32 v56, v55, v54
	v_fma_f32 v57, -v0, v56, v55
	v_fmac_f32_e32 v56, v57, v54
	v_fma_f32 v0, -v0, v56, v55
	v_div_fmas_f32 v0, v0, v54, v56
	v_div_fixup_f32 v50, v0, v50, 2.0
	v_pk_add_f32 v[50:51], v[50:51], 1.0 op_sel_hi:[1,0] neg_lo:[1,0] neg_hi:[1,0]
	s_nop 0
	v_pk_add_f32 v[50:51], v[50:51], 1.0 op_sel_hi:[1,0]
	s_nop 0
	v_pk_mul_f32 v[48:49], v[48:49], v[50:51]
	s_nop 0
	v_cvt_pk_bf16_f32 v47, v48, v49
	global_store_dwordx2 v[42:43], v[46:47], off offset:-4
	v_lshl_add_u64 v[42:43], v[42:43], 0, s[14:15]
	s_branch .Ls5p_sync1
.Ls5p_scan1:
	ds_read_b64 v[232:233], v97 offset:16384
	ds_read_b64 v[234:235], v97 offset:16896
	ds_read_b64 v[236:237], v97 offset:17408
	ds_read_b64 v[238:239], v97 offset:17920
	ds_read_b64 v[240:241], v253 offset:18432
	ds_read_b64 v[242:243], v253 offset:18944
	ds_read_b64 v[244:245], v253 offset:19456
	ds_read_b64 v[246:247], v253 offset:19968
	ds_read_b64 v[54:55], v254 offset:20480
	ds_read_b64 v[56:57], v254 offset:20992
	ds_read_b64 v[58:59], v254 offset:21504
	ds_read_b64 v[60:61], v254 offset:22016
	ds_read_b64 v[62:63], v255 offset:22528
	ds_read_b64 v[64:65], v255 offset:23040
	ds_read_b64 v[46:47], v255 offset:23552
	s_waitcnt lgkmcnt(8)
	ds_read_b64 v[48:49], v255 offset:24064
	ds_read_b64 v[168:169], v97 offset:24576
	ds_read_b64 v[170:171], v97 offset:25088
	ds_read_b64 v[172:173], v97 offset:25600
	ds_read_b64 v[174:175], v97 offset:26112
	ds_read_b64 v[176:177], v253 offset:26624
	ds_read_b64 v[178:179], v253 offset:27136
	s_waitcnt lgkmcnt(8)
	ds_read_b64 v[180:181], v253 offset:27648
	ds_read_b64 v[182:183], v253 offset:28160
	ds_read_b64 v[126:127], v254 offset:28672
	ds_read_b64 v[128:129], v254 offset:29184
	ds_read_b64 v[130:131], v254 offset:29696
	ds_read_b64 v[132:133], v254 offset:30208
	ds_read_b64 v[220:221], v255 offset:30720
	s_waitcnt lgkmcnt(8)
	ds_read_b64 v[222:223], v255 offset:31232
	ds_read_b64 v[224:225], v255 offset:31744
	ds_read_b64 v[226:227], v255 offset:32256
	v_fma_f32 v50, -v52, v45, v232
	v_fma_f32 v51, v52, v44, v233
	v_fma_f32 v44, v2, v44, v50
	v_fma_f32 v45, v2, v45, v51
	v_cvt_pk_bf16_f32 v0, v44, v45
	ds_write_b32 v229, v0 offset:41472
	v_fma_f32 v50, -v52, v45, v234
	v_fma_f32 v51, v52, v44, v235
	v_fma_f32 v44, v2, v44, v50
	v_fma_f32 v45, v2, v45, v51
	v_cvt_pk_bf16_f32 v66, v44, v45
	ds_write_b32 v229, v66 offset:41744
	v_fma_f32 v50, -v52, v45, v236
	v_fma_f32 v51, v52, v44, v237
	v_fma_f32 v44, v2, v44, v50
	v_fma_f32 v45, v2, v45, v51
	v_cvt_pk_bf16_f32 v0, v44, v45
	ds_write_b32 v229, v0 offset:42016
	v_fma_f32 v50, -v52, v45, v238
	v_fma_f32 v51, v52, v44, v239
	v_fma_f32 v44, v2, v44, v50
	v_fma_f32 v45, v2, v45, v51
	v_cvt_pk_bf16_f32 v66, v44, v45
	ds_write_b32 v229, v66 offset:42288
	v_fma_f32 v50, -v52, v45, v240
	v_fma_f32 v51, v52, v44, v241
	v_fma_f32 v44, v2, v44, v50
	v_fma_f32 v45, v2, v45, v51
	v_cvt_pk_bf16_f32 v0, v44, v45
	s_waitcnt lgkmcnt(8)
	ds_write_b32 v229, v0 offset:42560
	v_fma_f32 v50, -v52, v45, v242
	v_fma_f32 v51, v52, v44, v243
	v_fma_f32 v44, v2, v44, v50
	v_fma_f32 v45, v2, v45, v51
	v_cvt_pk_bf16_f32 v66, v44, v45
	ds_write_b32 v229, v66 offset:42832
	v_fma_f32 v50, -v52, v45, v244
	v_fma_f32 v51, v52, v44, v245
	v_fma_f32 v44, v2, v44, v50
	v_fma_f32 v45, v2, v45, v51
	v_cvt_pk_bf16_f32 v0, v44, v45
	ds_write_b32 v229, v0 offset:43104
	v_fma_f32 v50, -v52, v45, v246
	v_fma_f32 v51, v52, v44, v247
	v_fma_f32 v44, v2, v44, v50
	v_fma_f32 v45, v2, v45, v51
	v_cvt_pk_bf16_f32 v66, v44, v45
	ds_write_b32 v229, v66 offset:43376
	v_fma_f32 v50, -v52, v45, v54
	v_fma_f32 v51, v52, v44, v55
	v_fma_f32 v44, v2, v44, v50
	v_fma_f32 v45, v2, v45, v51
	v_cvt_pk_bf16_f32 v0, v44, v45
	ds_write_b32 v229, v0 offset:43648
	v_fma_f32 v50, -v52, v45, v56
	v_fma_f32 v51, v52, v44, v57
	v_fma_f32 v44, v2, v44, v50
	v_fma_f32 v45, v2, v45, v51
	v_cvt_pk_bf16_f32 v66, v44, v45
	ds_write_b32 v229, v66 offset:43920
	v_fma_f32 v50, -v52, v45, v58
	v_fma_f32 v51, v52, v44, v59
	v_fma_f32 v44, v2, v44, v50
	v_fma_f32 v45, v2, v45, v51
	v_cvt_pk_bf16_f32 v0, v44, v45
	ds_write_b32 v229, v0 offset:44192
	v_fma_f32 v50, -v52, v45, v60
	v_fma_f32 v51, v52, v44, v61
	v_fma_f32 v44, v2, v44, v50
	v_fma_f32 v45, v2, v45, v51
	v_cvt_pk_bf16_f32 v66, v44, v45
	s_waitcnt lgkmcnt(8)
	ds_write_b32 v229, v66 offset:44464
	v_fma_f32 v50, -v52, v45, v62
	v_fma_f32 v51, v52, v44, v63
	v_fma_f32 v44, v2, v44, v50
	v_fma_f32 v45, v2, v45, v51
	v_cvt_pk_bf16_f32 v0, v44, v45
	ds_write_b32 v229, v0 offset:44736
	v_fma_f32 v50, -v52, v45, v64
	v_fma_f32 v51, v52, v44, v65
	v_fma_f32 v44, v2, v44, v50
	v_fma_f32 v45, v2, v45, v51
	v_cvt_pk_bf16_f32 v66, v44, v45
	ds_write_b32 v229, v66 offset:45008
	v_fma_f32 v50, -v52, v45, v46
	v_fma_f32 v51, v52, v44, v47
	v_fma_f32 v44, v2, v44, v50
	v_fma_f32 v45, v2, v45, v51
	v_cvt_pk_bf16_f32 v0, v44, v45
	ds_write_b32 v229, v0 offset:45280
	v_fma_f32 v50, -v52, v45, v48
	v_fma_f32 v51, v52, v44, v49
	v_fma_f32 v44, v2, v44, v50
	v_fma_f32 v45, v2, v45, v51
	v_cvt_pk_bf16_f32 v66, v44, v45
	ds_write_b32 v229, v66 offset:45552
	v_fma_f32 v50, -v52, v45, v168
	v_fma_f32 v51, v52, v44, v169
	v_fma_f32 v44, v2, v44, v50
	v_fma_f32 v45, v2, v45, v51
	v_cvt_pk_bf16_f32 v0, v44, v45
	ds_write_b32 v229, v0 offset:45824
	v_fma_f32 v50, -v52, v45, v170
	v_fma_f32 v51, v52, v44, v171
	v_fma_f32 v44, v2, v44, v50
	v_fma_f32 v45, v2, v45, v51
	v_cvt_pk_bf16_f32 v66, v44, v45
	ds_write_b32 v229, v66 offset:46096
	v_fma_f32 v50, -v52, v45, v172
	v_fma_f32 v51, v52, v44, v173
	v_fma_f32 v44, v2, v44, v50
	v_fma_f32 v45, v2, v45, v51
	v_cvt_pk_bf16_f32 v0, v44, v45
	s_waitcnt lgkmcnt(8)
	ds_write_b32 v229, v0 offset:46368
	v_fma_f32 v50, -v52, v45, v174
	v_fma_f32 v51, v52, v44, v175
	v_fma_f32 v44, v2, v44, v50
	v_fma_f32 v45, v2, v45, v51
	v_cvt_pk_bf16_f32 v66, v44, v45
	ds_write_b32 v229, v66 offset:46640
	v_fma_f32 v50, -v52, v45, v176
	v_fma_f32 v51, v52, v44, v177
	v_fma_f32 v44, v2, v44, v50
	v_fma_f32 v45, v2, v45, v51
	v_cvt_pk_bf16_f32 v0, v44, v45
	ds_write_b32 v229, v0 offset:46912
	v_fma_f32 v50, -v52, v45, v178
	v_fma_f32 v51, v52, v44, v179
	v_fma_f32 v44, v2, v44, v50
	v_fma_f32 v45, v2, v45, v51
	v_cvt_pk_bf16_f32 v66, v44, v45
	ds_write_b32 v229, v66 offset:47184
	v_fma_f32 v50, -v52, v45, v180
	v_fma_f32 v51, v52, v44, v181
	v_fma_f32 v44, v2, v44, v50
	v_fma_f32 v45, v2, v45, v51
	v_cvt_pk_bf16_f32 v0, v44, v45
	ds_write_b32 v229, v0 offset:47456
	v_fma_f32 v50, -v52, v45, v182
	v_fma_f32 v51, v52, v44, v183
	v_fma_f32 v44, v2, v44, v50
	v_fma_f32 v45, v2, v45, v51
	v_cvt_pk_bf16_f32 v66, v44, v45
	ds_write_b32 v229, v66 offset:47728
	v_fma_f32 v50, -v52, v45, v126
	v_fma_f32 v51, v52, v44, v127
	v_fma_f32 v44, v2, v44, v50
	v_fma_f32 v45, v2, v45, v51
	v_cvt_pk_bf16_f32 v0, v44, v45
	ds_write_b32 v229, v0 offset:48000
	v_fma_f32 v50, -v52, v45, v128
	v_fma_f32 v51, v52, v44, v129
	v_fma_f32 v44, v2, v44, v50
	v_fma_f32 v45, v2, v45, v51
	v_cvt_pk_bf16_f32 v66, v44, v45
	s_waitcnt lgkmcnt(8)
	ds_write_b32 v229, v66 offset:48272
	v_fma_f32 v50, -v52, v45, v130
	v_fma_f32 v51, v52, v44, v131
	v_fma_f32 v44, v2, v44, v50
	v_fma_f32 v45, v2, v45, v51
	v_cvt_pk_bf16_f32 v0, v44, v45
	ds_write_b32 v229, v0 offset:48544
	v_fma_f32 v50, -v52, v45, v132
	v_fma_f32 v51, v52, v44, v133
	v_fma_f32 v44, v2, v44, v50
	v_fma_f32 v45, v2, v45, v51
	v_cvt_pk_bf16_f32 v66, v44, v45
	ds_write_b32 v229, v66 offset:48816
	v_fma_f32 v50, -v52, v45, v220
	v_fma_f32 v51, v52, v44, v221
	v_fma_f32 v44, v2, v44, v50
	v_fma_f32 v45, v2, v45, v51
	v_cvt_pk_bf16_f32 v0, v44, v45
	ds_write_b32 v229, v0 offset:49088
	v_fma_f32 v50, -v52, v45, v222
	v_fma_f32 v51, v52, v44, v223
	v_fma_f32 v44, v2, v44, v50
	v_fma_f32 v45, v2, v45, v51
	v_cvt_pk_bf16_f32 v66, v44, v45
	ds_write_b32 v229, v66 offset:49360
	v_fma_f32 v50, -v52, v45, v224
	v_fma_f32 v51, v52, v44, v225
	v_fma_f32 v44, v2, v44, v50
	v_fma_f32 v45, v2, v45, v51
	v_cvt_pk_bf16_f32 v0, v44, v45
	ds_write_b32 v229, v0 offset:49632
	v_fma_f32 v50, -v52, v45, v226
	v_fma_f32 v51, v52, v44, v227
	v_fma_f32 v44, v2, v44, v50
	v_fma_f32 v45, v2, v45, v51
	v_cvt_pk_bf16_f32 v66, v44, v45
	ds_write_b32 v229, v66 offset:49904
	s_branch .Ls5p_sync1
.Ls5p_bu1:
	s_cmp_lt_u32 s98, 15
	s_cbranch_scc0 .Ls5p_last1
	s_waitcnt vmcnt(1)
	ds_write_b128 v230, v[210:213] offset:57856
	global_load_dwordx4 v[210:213], v[248:249], off
	v_lshl_add_u64 v[248:249], v[248:249], 0, s[0:1]
	s_branch .Ls5p_cont1
.Ls5p_last1:
	s_waitcnt vmcnt(0)
	ds_write_b128 v230, v[210:213] offset:57856
.Ls5p_cont1:
	ds_read_b128 v[46:49], v203 offset:55296
	ds_read_b128 v[54:57], v203 offset:56576
	s_waitcnt lgkmcnt(1)
	v_mfma_f32_16x16x32_bf16 v[58:61], v[46:49], v[168:171], 0
	v_mfma_f32_16x16x32_bf16 v[62:65], v[46:49], v[172:175], 0
	v_add_u32_e32 v0, 0x0, v214
	v_add_u32_e32 v50, 0x400, v214
	v_mfma_f32_16x16x32_bf16 v[122:125], v[46:49], v[176:179], 0
	v_mfma_f32_16x16x32_bf16 v[198:201], v[46:49], v[180:183], 0
	v_add_u32_e32 v51, 0x0, v216
	v_add_u32_e32 v66, 0x400, v216
	v_mfma_f32_16x16x32_bf16 v[232:235], v[46:49], v[126:129], 0
	v_mfma_f32_16x16x32_bf16 v[236:239], v[46:49], v[130:133], 0
	v_add_u32_e32 v253, 0x0, v217
	v_add_u32_e32 v254, 0x400, v217
	v_mfma_f32_16x16x32_bf16 v[240:243], v[46:49], v[220:223], 0
	v_mfma_f32_16x16x32_bf16 v[244:247], v[46:49], v[224:227], 0
	v_add_u32_e32 v255, 0x0, v218
	v_add_u32_e32 v113, 0x400, v218
	s_nop 3
	ds_write2_b32 v0, v58, v62 offset1:16
	ds_write2_b32 v0, v59, v63 offset0:128 offset1:144
	ds_write2_b32 v50, v60, v64 offset1:16
	ds_write2_b32 v50, v61, v65 offset0:128 offset1:144
	ds_write2_b32 v51, v122, v198 offset1:16
	ds_write2_b32 v51, v123, v199 offset0:128 offset1:144
	ds_write2_b32 v66, v124, v200 offset1:16
	ds_write2_b32 v66, v125, v201 offset0:128 offset1:144
	ds_write2_b32 v253, v232, v236 offset1:16
	ds_write2_b32 v253, v233, v237 offset0:128 offset1:144
	ds_write2_b32 v254, v234, v238 offset1:16
	ds_write2_b32 v254, v235, v239 offset0:128 offset1:144
	ds_write2_b32 v255, v240, v244 offset1:16
	ds_write2_b32 v255, v241, v245 offset0:128 offset1:144
	ds_write2_b32 v113, v242, v246 offset1:16
	ds_write2_b32 v113, v243, v247 offset0:128 offset1:144
	s_waitcnt lgkmcnt(0)
	v_mfma_f32_16x16x32_bf16 v[58:61], v[54:57], v[168:171], 0
	v_mfma_f32_16x16x32_bf16 v[62:65], v[54:57], v[172:175], 0
	v_add_u32_e32 v0, 0x2000, v214
	v_add_u32_e32 v50, 0x2400, v214
	v_mfma_f32_16x16x32_bf16 v[122:125], v[54:57], v[176:179], 0
	v_mfma_f32_16x16x32_bf16 v[198:201], v[54:57], v[180:183], 0
	v_add_u32_e32 v51, 0x2000, v216
	v_add_u32_e32 v66, 0x2400, v216
	v_mfma_f32_16x16x32_bf16 v[232:235], v[54:57], v[126:129], 0
	v_mfma_f32_16x16x32_bf16 v[236:239], v[54:57], v[130:133], 0
	v_add_u32_e32 v253, 0x2000, v217
	v_add_u32_e32 v254, 0x2400, v217
	v_mfma_f32_16x16x32_bf16 v[240:243], v[54:57], v[220:223], 0
	v_mfma_f32_16x16x32_bf16 v[244:247], v[54:57], v[224:227], 0
	v_add_u32_e32 v255, 0x2000, v218
	v_add_u32_e32 v113, 0x2400, v218
	s_nop 3
	ds_write2_b32 v0, v58, v62 offset1:16
	ds_write2_b32 v0, v59, v63 offset0:128 offset1:144
	ds_write2_b32 v50, v60, v64 offset1:16
	ds_write2_b32 v50, v61, v65 offset0:128 offset1:144
	ds_write2_b32 v51, v122, v198 offset1:16
	ds_write2_b32 v51, v123, v199 offset0:128 offset1:144
	ds_write2_b32 v66, v124, v200 offset1:16
	ds_write2_b32 v66, v125, v201 offset0:128 offset1:144
	ds_write2_b32 v253, v232, v236 offset1:16
	ds_write2_b32 v253, v233, v237 offset0:128 offset1:144
	ds_write2_b32 v254, v234, v238 offset1:16
	ds_write2_b32 v254, v235, v239 offset0:128 offset1:144
	ds_write2_b32 v255, v240, v244 offset1:16
	ds_write2_b32 v255, v241, v245 offset0:128 offset1:144
	ds_write2_b32 v113, v242, v246 offset1:16
	ds_write2_b32 v113, v243, v247 offset0:128 offset1:144
.Ls5p_sync1:
	s_waitcnt lgkmcnt(0)
	s_barrier
	s_cmp_eq_u32 s99, 0
	s_cbranch_scc1 .Ls5p_scan2
	s_cmp_eq_u32 s99, 1
	s_cbranch_scc1 .Ls5p_bu2
	ds_read_b128 v[46:49], v231 offset:41472
	ds_read_b128 v[54:57], v231 offset:41536
	s_waitcnt lgkmcnt(1)
	v_mfma_f32_16x16x32_bf16 v[46:49], v[20:23], v[46:49], 0
	ds_read_b64 v[50:51], v53 offset:52736
	s_waitcnt lgkmcnt(1)
	v_mfma_f32_16x16x32_bf16 v[46:49], v[24:27], v[54:57], v[46:49]
	ds_read_b128 v[54:57], v231 offset:41600
	s_waitcnt lgkmcnt(0)
	v_mfma_f32_16x16x32_bf16 v[46:49], v[28:31], v[54:57], v[46:49]
	ds_read_b128 v[54:57], v231 offset:41664
	s_waitcnt lgkmcnt(0)
	v_mfma_f32_16x16x32_bf16 v[46:49], v[32:35], v[54:57], v[46:49]
	v_lshlrev_b32_e32 v54, 16, v50
	v_and_b32_e32 v55, 0xffff0000, v50
	s_nop 0
	s_nop 4
	v_pk_fma_f32 v[46:47], v[8:9], v[54:55], v[46:47]
	s_nop 0
	v_mul_f32_e32 v0, 0x3d372713, v46
	v_mul_f32_e32 v0, v46, v0
	v_fma_f32 v0, v46, v0, v46
	v_mul_f32_e32 v0, 0x3f4c422a, v0
	v_add_f32_e32 v0, v0, v0
	v_mul_f32_e32 v0, 0x3fb8aa3b, v0
	v_exp_f32_e32 v54, v0
	v_mul_f32_e32 v0, 0x3d372713, v47
	v_mul_f32_e32 v0, v47, v0
	v_fma_f32 v0, v47, v0, v47
	v_mul_f32_e32 v0, 0x3f4c422a, v0
	v_add_f32_e32 v0, v0, v0
	v_mul_f32_e32 v0, 0x3fb8aa3b, v0
	v_exp_f32_e32 v55, v0
	v_pk_mul_f32 v[46:47], v[46:47], 0.5 op_sel_hi:[1,0]
	v_pk_add_f32 v[54:55], v[54:55], 1.0 op_sel_hi:[1,0]
	s_nop 0
	v_div_scale_f32 v0, s[14:15], v55, v55, 2.0
	v_rcp_f32_e32 v50, v0
	s_nop 0
	v_fma_f32 v56, -v0, v50, 1.0
	v_fmac_f32_e32 v50, v56, v50
	v_div_scale_f32 v56, vcc, 2.0, v55, 2.0
	v_mul_f32_e32 v57, v56, v50
	v_fma_f32 v58, -v0, v57, v56
	v_fmac_f32_e32 v57, v58, v50
	v_fma_f32 v0, -v0, v57, v56
	v_div_fmas_f32 v0, v0, v50, v57
	v_div_fixup_f32 v55, v0, v55, 2.0
	v_div_scale_f32 v0, s[14:15], v54, v54, 2.0
	v_rcp_f32_e32 v50, v0
	s_nop 0
	v_fma_f32 v56, -v0, v50, 1.0
	v_fmac_f32_e32 v50, v56, v50
	v_div_scale_f32 v56, vcc, 2.0, v54, 2.0
	v_mul_f32_e32 v57, v56, v50
	v_fma_f32 v58, -v0, v57, v56
	v_fmac_f32_e32 v57, v58, v50
	v_fma_f32 v0, -v0, v57, v56
	v_div_fmas_f32 v0, v0, v50, v57
	v_lshlrev_b32_e32 v50, 16, v51
	v_and_b32_e32 v51, 0xffff0000, v51
	v_pk_fma_f32 v[48:49], v[10:11], v[50:51], v[48:49]
	v_div_fixup_f32 v54, v0, v54, 2.0
	v_mul_f32_e32 v0, 0x3d372713, v48
	v_mul_f32_e32 v0, v48, v0
	v_fma_f32 v0, v48, v0, v48
	v_mul_f32_e32 v0, 0x3f4c422a, v0
	v_add_f32_e32 v0, v0, v0
	v_mul_f32_e32 v0, 0x3fb8aa3b, v0
	v_exp_f32_e32 v50, v0
	v_mul_f32_e32 v0, 0x3d372713, v49
	v_mul_f32_e32 v0, v49, v0
	v_fma_f32 v0, v49, v0, v49
	v_mul_f32_e32 v0, 0x3f4c422a, v0
	v_add_f32_e32 v0, v0, v0
	v_mul_f32_e32 v0, 0x3fb8aa3b, v0
	v_exp_f32_e32 v51, v0
	v_pk_add_f32 v[54:55], v[54:55], 1.0 op_sel_hi:[1,0] neg_lo:[1,0] neg_hi:[1,0]
	v_pk_mul_f32 v[48:49], v[48:49], 0.5 op_sel_hi:[1,0]
	v_pk_add_f32 v[54:55], v[54:55], 1.0 op_sel_hi:[1,0]
	v_pk_add_f32 v[50:51], v[50:51], 1.0 op_sel_hi:[1,0]
	v_pk_mul_f32 v[46:47], v[46:47], v[54:55]
	v_div_scale_f32 v0, s[14:15], v51, v51, 2.0
	v_rcp_f32_e32 v54, v0
	v_cvt_pk_bf16_f32 v46, v46, v47
	v_fma_f32 v55, -v0, v54, 1.0
	v_fmac_f32_e32 v54, v55, v54
	v_div_scale_f32 v55, vcc, 2.0, v51, 2.0
	v_mul_f32_e32 v56, v55, v54
	v_fma_f32 v57, -v0, v56, v55
	v_fmac_f32_e32 v56, v57, v54
	v_fma_f32 v0, -v0, v56, v55
	v_div_fmas_f32 v0, v0, v54, v56
	v_div_fixup_f32 v51, v0, v51, 2.0
	v_div_scale_f32 v0, s[14:15], v50, v50, 2.0
	v_rcp_f32_e32 v54, v0
	s_mov_b64 s[14:15], 0x8000
	v_fma_f32 v55, -v0, v54, 1.0
	v_fmac_f32_e32 v54, v55, v54
	v_div_scale_f32 v55, vcc, 2.0, v50, 2.0
	v_mul_f32_e32 v56, v55, v54
	v_fma_f32 v57, -v0, v56, v55
	v_fmac_f32_e32 v56, v57, v54
	v_fma_f32 v0, -v0, v56, v55
	v_div_fmas_f32 v0, v0, v54, v56
	v_div_fixup_f32 v50, v0, v50, 2.0
	v_pk_add_f32 v[50:51], v[50:51], 1.0 op_sel_hi:[1,0] neg_lo:[1,0] neg_hi:[1,0]
	s_nop 0
	v_pk_add_f32 v[50:51], v[50:51], 1.0 op_sel_hi:[1,0]
	s_nop 0
	v_pk_mul_f32 v[48:49], v[48:49], v[50:51]
	s_nop 0
	v_cvt_pk_bf16_f32 v47, v48, v49
	global_store_dwordx2 v[42:43], v[46:47], off offset:-4
	v_lshl_add_u64 v[42:43], v[42:43], 0, s[14:15]
	s_branch .Ls5p_sync2

.Ls5p_bu2:
	s_cmp_lt_u32 s98, 15
	s_cbranch_scc0 .Ls5p_last2
	s_waitcnt vmcnt(1)
	ds_write_b128 v230, v[12:15] offset:50176
	global_load_dwordx4 v[12:15], v[248:249], off
	v_lshl_add_u64 v[248:249], v[248:249], 0, s[0:1]
	s_branch .Ls5p_cont2
.Ls5p_last2:
	s_waitcnt vmcnt(0)
	ds_write_b128 v230, v[12:15] offset:50176
.Ls5p_cont2:
	ds_read_b128 v[46:49], v203 offset:57856
	ds_read_b128 v[54:57], v203 offset:59136
	s_waitcnt lgkmcnt(1)
	v_mfma_f32_16x16x32_bf16 v[58:61], v[46:49], v[168:171], 0
	v_mfma_f32_16x16x32_bf16 v[62:65], v[46:49], v[172:175], 0
	v_add_u32_e32 v0, 0x4000, v214
	v_add_u32_e32 v50, 0x4400, v214
	v_mfma_f32_16x16x32_bf16 v[122:125], v[46:49], v[176:179], 0
	v_mfma_f32_16x16x32_bf16 v[198:201], v[46:49], v[180:183], 0
	v_add_u32_e32 v51, 0x4000, v216
	v_add_u32_e32 v66, 0x4400, v216
	v_mfma_f32_16x16x32_bf16 v[232:235], v[46:49], v[126:129], 0
	v_mfma_f32_16x16x32_bf16 v[236:239], v[46:49], v[130:133], 0
	v_add_u32_e32 v253, 0x4000, v217
	v_add_u32_e32 v254, 0x4400, v217
	v_mfma_f32_16x16x32_bf16 v[240:243], v[46:49], v[220:223], 0
	v_mfma_f32_16x16x32_bf16 v[244:247], v[46:49], v[224:227], 0
	v_add_u32_e32 v255, 0x4000, v218
	v_add_u32_e32 v113, 0x4400, v218
	s_nop 3
	ds_write2_b32 v0, v58, v62 offset1:16
	ds_write2_b32 v0, v59, v63 offset0:128 offset1:144
	ds_write2_b32 v50, v60, v64 offset1:16
	ds_write2_b32 v50, v61, v65 offset0:128 offset1:144
	ds_write2_b32 v51, v122, v198 offset1:16
	ds_write2_b32 v51, v123, v199 offset0:128 offset1:144
	ds_write2_b32 v66, v124, v200 offset1:16
	ds_write2_b32 v66, v125, v201 offset0:128 offset1:144
	ds_write2_b32 v253, v232, v236 offset1:16
	ds_write2_b32 v253, v233, v237 offset0:128 offset1:144
	ds_write2_b32 v254, v234, v238 offset1:16
	ds_write2_b32 v254, v235, v239 offset0:128 offset1:144
	ds_write2_b32 v255, v240, v244 offset1:16
	ds_write2_b32 v255, v241, v245 offset0:128 offset1:144
	ds_write2_b32 v113, v242, v246 offset1:16
	ds_write2_b32 v113, v243, v247 offset0:128 offset1:144
	s_waitcnt lgkmcnt(0)
	v_mfma_f32_16x16x32_bf16 v[58:61], v[54:57], v[168:171], 0
	v_mfma_f32_16x16x32_bf16 v[62:65], v[54:57], v[172:175], 0
	v_add_u32_e32 v0, 0x6000, v214
	v_add_u32_e32 v50, 0x6400, v214
	v_mfma_f32_16x16x32_bf16 v[122:125], v[54:57], v[176:179], 0
	v_mfma_f32_16x16x32_bf16 v[198:201], v[54:57], v[180:183], 0
	v_add_u32_e32 v51, 0x6000, v216
	v_add_u32_e32 v66, 0x6400, v216
	v_mfma_f32_16x16x32_bf16 v[232:235], v[54:57], v[126:129], 0
	v_mfma_f32_16x16x32_bf16 v[236:239], v[54:57], v[130:133], 0
	v_add_u32_e32 v253, 0x6000, v217
	v_add_u32_e32 v254, 0x6400, v217
	v_mfma_f32_16x16x32_bf16 v[240:243], v[54:57], v[220:223], 0
	v_mfma_f32_16x16x32_bf16 v[244:247], v[54:57], v[224:227], 0
	v_add_u32_e32 v255, 0x6000, v218
	v_add_u32_e32 v113, 0x6400, v218
	s_nop 3
	ds_write2_b32 v0, v58, v62 offset1:16
	ds_write2_b32 v0, v59, v63 offset0:128 offset1:144
	ds_write2_b32 v50, v60, v64 offset1:16
	ds_write2_b32 v50, v61, v65 offset0:128 offset1:144
	ds_write2_b32 v51, v122, v198 offset1:16
	ds_write2_b32 v51, v123, v199 offset0:128 offset1:144
	ds_write2_b32 v66, v124, v200 offset1:16
	ds_write2_b32 v66, v125, v201 offset0:128 offset1:144
	ds_write2_b32 v253, v232, v236 offset1:16
	ds_write2_b32 v253, v233, v237 offset0:128 offset1:144
	ds_write2_b32 v254, v234, v238 offset1:16
	ds_write2_b32 v254, v235, v239 offset0:128 offset1:144
	ds_write2_b32 v255, v240, v244 offset1:16
	ds_write2_b32 v255, v241, v245 offset0:128 offset1:144
	ds_write2_b32 v113, v242, v246 offset1:16
	ds_write2_b32 v113, v243, v247 offset0:128 offset1:144
.Ls5p_sync2:
	s_waitcnt lgkmcnt(0)
	s_barrier
	s_cmp_eq_u32 s99, 0
	s_cbranch_scc1 .Ls5p_scan3
	s_cmp_eq_u32 s99, 1
	s_cbranch_scc1 .Ls5p_bu3
	ds_read_b128 v[46:49], v231 offset:32768
	ds_read_b128 v[54:57], v231 offset:32832
	s_waitcnt lgkmcnt(1)
	v_mfma_f32_16x16x32_bf16 v[46:49], v[20:23], v[46:49], 0
	ds_read_b64 v[50:51], v53 offset:55296
	s_waitcnt lgkmcnt(1)
	v_mfma_f32_16x16x32_bf16 v[46:49], v[24:27], v[54:57], v[46:49]
	ds_read_b128 v[54:57], v231 offset:32896
	s_waitcnt lgkmcnt(0)
	v_mfma_f32_16x16x32_bf16 v[46:49], v[28:31], v[54:57], v[46:49]
	ds_read_b128 v[54:57], v231 offset:32960
	s_waitcnt lgkmcnt(0)
	v_mfma_f32_16x16x32_bf16 v[46:49], v[32:35], v[54:57], v[46:49]
	v_lshlrev_b32_e32 v54, 16, v50
	v_and_b32_e32 v55, 0xffff0000, v50
	s_nop 0
	s_nop 4
	v_pk_fma_f32 v[46:47], v[8:9], v[54:55], v[46:47]
	s_nop 0
	v_mul_f32_e32 v0, 0x3d372713, v46
	v_mul_f32_e32 v0, v46, v0
	v_fma_f32 v0, v46, v0, v46
	v_mul_f32_e32 v0, 0x3f4c422a, v0
	v_add_f32_e32 v0, v0, v0
	v_mul_f32_e32 v0, 0x3fb8aa3b, v0
	v_exp_f32_e32 v54, v0
	v_mul_f32_e32 v0, 0x3d372713, v47
	v_mul_f32_e32 v0, v47, v0
	v_fma_f32 v0, v47, v0, v47
	v_mul_f32_e32 v0, 0x3f4c422a, v0
	v_add_f32_e32 v0, v0, v0
	v_mul_f32_e32 v0, 0x3fb8aa3b, v0
	v_exp_f32_e32 v55, v0
	v_pk_mul_f32 v[46:47], v[46:47], 0.5 op_sel_hi:[1,0]
	v_pk_add_f32 v[54:55], v[54:55], 1.0 op_sel_hi:[1,0]
	s_nop 0
	v_div_scale_f32 v0, s[14:15], v55, v55, 2.0
	v_rcp_f32_e32 v50, v0
	s_nop 0
	v_fma_f32 v56, -v0, v50, 1.0
	v_fmac_f32_e32 v50, v56, v50
	v_div_scale_f32 v56, vcc, 2.0, v55, 2.0
	v_mul_f32_e32 v57, v56, v50
	v_fma_f32 v58, -v0, v57, v56
	v_fmac_f32_e32 v57, v58, v50
	v_fma_f32 v0, -v0, v57, v56
	v_div_fmas_f32 v0, v0, v50, v57
	v_div_fixup_f32 v55, v0, v55, 2.0
	v_div_scale_f32 v0, s[14:15], v54, v54, 2.0
	v_rcp_f32_e32 v50, v0
	s_nop 0
	v_fma_f32 v56, -v0, v50, 1.0
	v_fmac_f32_e32 v50, v56, v50
	v_div_scale_f32 v56, vcc, 2.0, v54, 2.0
	v_mul_f32_e32 v57, v56, v50
	v_fma_f32 v58, -v0, v57, v56
	v_fmac_f32_e32 v57, v58, v50
	v_fma_f32 v0, -v0, v57, v56
	v_div_fmas_f32 v0, v0, v50, v57
	v_lshlrev_b32_e32 v50, 16, v51
	v_and_b32_e32 v51, 0xffff0000, v51
	v_pk_fma_f32 v[48:49], v[10:11], v[50:51], v[48:49]
	v_div_fixup_f32 v54, v0, v54, 2.0
	v_mul_f32_e32 v0, 0x3d372713, v48
	v_mul_f32_e32 v0, v48, v0
	v_fma_f32 v0, v48, v0, v48
	v_mul_f32_e32 v0, 0x3f4c422a, v0
	v_add_f32_e32 v0, v0, v0
	v_mul_f32_e32 v0, 0x3fb8aa3b, v0
	v_exp_f32_e32 v50, v0
	v_mul_f32_e32 v0, 0x3d372713, v49
	v_mul_f32_e32 v0, v49, v0
	v_fma_f32 v0, v49, v0, v49
	v_mul_f32_e32 v0, 0x3f4c422a, v0
	v_add_f32_e32 v0, v0, v0
	v_mul_f32_e32 v0, 0x3fb8aa3b, v0
	v_exp_f32_e32 v51, v0
	v_pk_add_f32 v[54:55], v[54:55], 1.0 op_sel_hi:[1,0] neg_lo:[1,0] neg_hi:[1,0]
	v_pk_mul_f32 v[48:49], v[48:49], 0.5 op_sel_hi:[1,0]
	v_pk_add_f32 v[54:55], v[54:55], 1.0 op_sel_hi:[1,0]
	v_pk_add_f32 v[50:51], v[50:51], 1.0 op_sel_hi:[1,0]
	v_pk_mul_f32 v[46:47], v[46:47], v[54:55]
	v_div_scale_f32 v0, s[14:15], v51, v51, 2.0
	v_rcp_f32_e32 v54, v0
	v_cvt_pk_bf16_f32 v46, v46, v47
	v_fma_f32 v55, -v0, v54, 1.0
	v_fmac_f32_e32 v54, v55, v54
	v_div_scale_f32 v55, vcc, 2.0, v51, 2.0
	v_mul_f32_e32 v56, v55, v54
	v_fma_f32 v57, -v0, v56, v55
	v_fmac_f32_e32 v56, v57, v54
	v_fma_f32 v0, -v0, v56, v55
	v_div_fmas_f32 v0, v0, v54, v56
	v_div_fixup_f32 v51, v0, v51, 2.0
	v_div_scale_f32 v0, s[14:15], v50, v50, 2.0
	v_rcp_f32_e32 v54, v0
	s_mov_b64 s[14:15], 0x8000
	v_fma_f32 v55, -v0, v54, 1.0
	v_fmac_f32_e32 v54, v55, v54
	v_div_scale_f32 v55, vcc, 2.0, v50, 2.0
	v_mul_f32_e32 v56, v55, v54
	v_fma_f32 v57, -v0, v56, v55
	v_fmac_f32_e32 v56, v57, v54
	v_fma_f32 v0, -v0, v56, v55
	v_div_fmas_f32 v0, v0, v54, v56
	v_div_fixup_f32 v50, v0, v50, 2.0
	v_pk_add_f32 v[50:51], v[50:51], 1.0 op_sel_hi:[1,0] neg_lo:[1,0] neg_hi:[1,0]
	s_nop 0
	v_pk_add_f32 v[50:51], v[50:51], 1.0 op_sel_hi:[1,0]
	s_nop 0
	v_pk_mul_f32 v[48:49], v[48:49], v[50:51]
	s_nop 0
	v_cvt_pk_bf16_f32 v47, v48, v49
	global_store_dwordx2 v[42:43], v[46:47], off offset:-4
	v_lshl_add_u64 v[42:43], v[42:43], 0, s[14:15]
	s_branch .Ls5p_sync3

.Ls5p_bu3:
	s_cmp_lt_u32 s98, 15
	s_cbranch_scc0 .Ls5p_last3
	s_waitcnt vmcnt(1)
	ds_write_b128 v230, v[210:213] offset:52736
	global_load_dwordx4 v[210:213], v[248:249], off
	v_lshl_add_u64 v[248:249], v[248:249], 0, s[0:1]
	s_branch .Ls5p_cont3
.Ls5p_last3:
	s_waitcnt vmcnt(0)
	ds_write_b128 v230, v[210:213] offset:52736
.Ls5p_cont3:
	ds_read_b128 v[46:49], v203 offset:50176
	ds_read_b128 v[54:57], v203 offset:51456
	s_waitcnt lgkmcnt(1)
	v_mfma_f32_16x16x32_bf16 v[58:61], v[46:49], v[168:171], 0
	v_mfma_f32_16x16x32_bf16 v[62:65], v[46:49], v[172:175], 0
	v_add_u32_e32 v0, 0x0, v214
	v_add_u32_e32 v50, 0x400, v214
	v_mfma_f32_16x16x32_bf16 v[122:125], v[46:49], v[176:179], 0
	v_mfma_f32_16x16x32_bf16 v[198:201], v[46:49], v[180:183], 0
	v_add_u32_e32 v51, 0x0, v216
	v_add_u32_e32 v66, 0x400, v216
	v_mfma_f32_16x16x32_bf16 v[232:235], v[46:49], v[126:129], 0
	v_mfma_f32_16x16x32_bf16 v[236:239], v[46:49], v[130:133], 0
	v_add_u32_e32 v253, 0x0, v217
	v_add_u32_e32 v254, 0x400, v217
	v_mfma_f32_16x16x32_bf16 v[240:243], v[46:49], v[220:223], 0
	v_mfma_f32_16x16x32_bf16 v[244:247], v[46:49], v[224:227], 0
	v_add_u32_e32 v255, 0x0, v218
	v_add_u32_e32 v113, 0x400, v218
	s_nop 3
	ds_write2_b32 v0, v58, v62 offset1:16
	ds_write2_b32 v0, v59, v63 offset0:128 offset1:144
	ds_write2_b32 v50, v60, v64 offset1:16
	ds_write2_b32 v50, v61, v65 offset0:128 offset1:144
	ds_write2_b32 v51, v122, v198 offset1:16
	ds_write2_b32 v51, v123, v199 offset0:128 offset1:144
	ds_write2_b32 v66, v124, v200 offset1:16
	ds_write2_b32 v66, v125, v201 offset0:128 offset1:144
	ds_write2_b32 v253, v232, v236 offset1:16
	ds_write2_b32 v253, v233, v237 offset0:128 offset1:144
	ds_write2_b32 v254, v234, v238 offset1:16
	ds_write2_b32 v254, v235, v239 offset0:128 offset1:144
	ds_write2_b32 v255, v240, v244 offset1:16
	ds_write2_b32 v255, v241, v245 offset0:128 offset1:144
	ds_write2_b32 v113, v242, v246 offset1:16
	ds_write2_b32 v113, v243, v247 offset0:128 offset1:144
	s_waitcnt lgkmcnt(0)
	v_mfma_f32_16x16x32_bf16 v[58:61], v[54:57], v[168:171], 0
	v_mfma_f32_16x16x32_bf16 v[62:65], v[54:57], v[172:175], 0
	v_add_u32_e32 v0, 0x2000, v214
	v_add_u32_e32 v50, 0x2400, v214
	v_mfma_f32_16x16x32_bf16 v[122:125], v[54:57], v[176:179], 0
	v_mfma_f32_16x16x32_bf16 v[198:201], v[54:57], v[180:183], 0
	v_add_u32_e32 v51, 0x2000, v216
	v_add_u32_e32 v66, 0x2400, v216
	v_mfma_f32_16x16x32_bf16 v[232:235], v[54:57], v[126:129], 0
	v_mfma_f32_16x16x32_bf16 v[236:239], v[54:57], v[130:133], 0
	v_add_u32_e32 v253, 0x2000, v217
	v_add_u32_e32 v254, 0x2400, v217
	v_mfma_f32_16x16x32_bf16 v[240:243], v[54:57], v[220:223], 0
	v_mfma_f32_16x16x32_bf16 v[244:247], v[54:57], v[224:227], 0
	v_add_u32_e32 v255, 0x2000, v218
	v_add_u32_e32 v113, 0x2400, v218
	s_nop 3
	ds_write2_b32 v0, v58, v62 offset1:16
	ds_write2_b32 v0, v59, v63 offset0:128 offset1:144
	ds_write2_b32 v50, v60, v64 offset1:16
	ds_write2_b32 v50, v61, v65 offset0:128 offset1:144
	ds_write2_b32 v51, v122, v198 offset1:16
	ds_write2_b32 v51, v123, v199 offset0:128 offset1:144
	ds_write2_b32 v66, v124, v200 offset1:16
	ds_write2_b32 v66, v125, v201 offset0:128 offset1:144
	ds_write2_b32 v253, v232, v236 offset1:16
	ds_write2_b32 v253, v233, v237 offset0:128 offset1:144
	ds_write2_b32 v254, v234, v238 offset1:16
	ds_write2_b32 v254, v235, v239 offset0:128 offset1:144
	ds_write2_b32 v255, v240, v244 offset1:16
	ds_write2_b32 v255, v241, v245 offset0:128 offset1:144
	ds_write2_b32 v113, v242, v246 offset1:16
	ds_write2_b32 v113, v243, v247 offset0:128 offset1:144
.Ls5p_sync3:
	s_waitcnt lgkmcnt(0)
	s_barrier
	s_add_u32 s98, s98, 1
	s_cmp_lt_u32 s98, 16
	s_cbranch_scc1 .Ls5p_loop
	s_cmp_lt_u32 s99, 2
	s_cbranch_scc1 .Ls5p_end
	ds_read_b128 v[46:49], v231 offset:41472
	ds_read_b128 v[54:57], v231 offset:41536
	s_waitcnt lgkmcnt(1)
	v_mfma_f32_16x16x32_bf16 v[46:49], v[20:23], v[46:49], 0
	ds_read_b64 v[50:51], v53 offset:57856
	s_waitcnt lgkmcnt(1)
	v_mfma_f32_16x16x32_bf16 v[46:49], v[24:27], v[54:57], v[46:49]
	ds_read_b128 v[54:57], v231 offset:41600
	s_waitcnt lgkmcnt(0)
	v_mfma_f32_16x16x32_bf16 v[46:49], v[28:31], v[54:57], v[46:49]
	ds_read_b128 v[54:57], v231 offset:41664
	s_waitcnt lgkmcnt(0)
	v_mfma_f32_16x16x32_bf16 v[46:49], v[32:35], v[54:57], v[46:49]
	v_lshlrev_b32_e32 v54, 16, v50
	v_and_b32_e32 v55, 0xffff0000, v50
	s_nop 0
	s_nop 4
	v_pk_fma_f32 v[46:47], v[8:9], v[54:55], v[46:47]
	s_nop 0
	v_mul_f32_e32 v0, 0x3d372713, v46
	v_mul_f32_e32 v0, v46, v0
	v_fma_f32 v0, v46, v0, v46
	v_mul_f32_e32 v0, 0x3f4c422a, v0
	v_add_f32_e32 v0, v0, v0
	v_mul_f32_e32 v0, 0x3fb8aa3b, v0
	v_exp_f32_e32 v54, v0
	v_mul_f32_e32 v0, 0x3d372713, v47
	v_mul_f32_e32 v0, v47, v0
	v_fma_f32 v0, v47, v0, v47
	v_mul_f32_e32 v0, 0x3f4c422a, v0
	v_add_f32_e32 v0, v0, v0
	v_mul_f32_e32 v0, 0x3fb8aa3b, v0
	v_exp_f32_e32 v55, v0
	v_pk_mul_f32 v[46:47], v[46:47], 0.5 op_sel_hi:[1,0]
	v_pk_add_f32 v[54:55], v[54:55], 1.0 op_sel_hi:[1,0]
	s_nop 0
	v_div_scale_f32 v0, s[14:15], v55, v55, 2.0
	v_rcp_f32_e32 v50, v0
	s_nop 0
	v_fma_f32 v56, -v0, v50, 1.0
	v_fmac_f32_e32 v50, v56, v50
	v_div_scale_f32 v56, vcc, 2.0, v55, 2.0
	v_mul_f32_e32 v57, v56, v50
	v_fma_f32 v58, -v0, v57, v56
	v_fmac_f32_e32 v57, v58, v50
	v_fma_f32 v0, -v0, v57, v56
	v_div_fmas_f32 v0, v0, v50, v57
	v_div_fixup_f32 v55, v0, v55, 2.0
	v_div_scale_f32 v0, s[14:15], v54, v54, 2.0
	v_rcp_f32_e32 v50, v0
	s_nop 0
	v_fma_f32 v56, -v0, v50, 1.0
	v_fmac_f32_e32 v50, v56, v50
	v_div_scale_f32 v56, vcc, 2.0, v54, 2.0
	v_mul_f32_e32 v57, v56, v50
	v_fma_f32 v58, -v0, v57, v56
	v_fmac_f32_e32 v57, v58, v50
	v_fma_f32 v0, -v0, v57, v56
	v_div_fmas_f32 v0, v0, v50, v57
	v_lshlrev_b32_e32 v50, 16, v51
	v_and_b32_e32 v51, 0xffff0000, v51
	v_pk_fma_f32 v[48:49], v[10:11], v[50:51], v[48:49]
	v_div_fixup_f32 v54, v0, v54, 2.0
	v_mul_f32_e32 v0, 0x3d372713, v48
	v_mul_f32_e32 v0, v48, v0
	v_fma_f32 v0, v48, v0, v48
	v_mul_f32_e32 v0, 0x3f4c422a, v0
	v_add_f32_e32 v0, v0, v0
	v_mul_f32_e32 v0, 0x3fb8aa3b, v0
	v_exp_f32_e32 v50, v0
	v_mul_f32_e32 v0, 0x3d372713, v49
	v_mul_f32_e32 v0, v49, v0
	v_fma_f32 v0, v49, v0, v49
	v_mul_f32_e32 v0, 0x3f4c422a, v0
	v_add_f32_e32 v0, v0, v0
	v_mul_f32_e32 v0, 0x3fb8aa3b, v0
	v_exp_f32_e32 v51, v0
	v_pk_add_f32 v[54:55], v[54:55], 1.0 op_sel_hi:[1,0] neg_lo:[1,0] neg_hi:[1,0]
	v_pk_mul_f32 v[48:49], v[48:49], 0.5 op_sel_hi:[1,0]
	v_pk_add_f32 v[54:55], v[54:55], 1.0 op_sel_hi:[1,0]
	v_pk_add_f32 v[50:51], v[50:51], 1.0 op_sel_hi:[1,0]
	v_pk_mul_f32 v[46:47], v[46:47], v[54:55]
	v_div_scale_f32 v0, s[14:15], v51, v51, 2.0
	v_rcp_f32_e32 v54, v0
	v_cvt_pk_bf16_f32 v46, v46, v47
	v_fma_f32 v55, -v0, v54, 1.0
	v_fmac_f32_e32 v54, v55, v54
	v_div_scale_f32 v55, vcc, 2.0, v51, 2.0
	v_mul_f32_e32 v56, v55, v54
	v_fma_f32 v57, -v0, v56, v55
	v_fmac_f32_e32 v56, v57, v54
	v_fma_f32 v0, -v0, v56, v55
	v_div_fmas_f32 v0, v0, v54, v56
	v_div_fixup_f32 v51, v0, v51, 2.0
	v_div_scale_f32 v0, s[14:15], v50, v50, 2.0
	v_rcp_f32_e32 v54, v0
	s_mov_b64 s[14:15], 0x8000
	v_fma_f32 v55, -v0, v54, 1.0
	v_fmac_f32_e32 v54, v55, v54
	v_div_scale_f32 v55, vcc, 2.0, v50, 2.0
	v_mul_f32_e32 v56, v55, v54
	v_fma_f32 v57, -v0, v56, v55
	v_fmac_f32_e32 v56, v57, v54
	v_fma_f32 v0, -v0, v56, v55
	v_div_fmas_f32 v0, v0, v54, v56
	v_div_fixup_f32 v50, v0, v50, 2.0
	v_pk_add_f32 v[50:51], v[50:51], 1.0 op_sel_hi:[1,0] neg_lo:[1,0] neg_hi:[1,0]
	s_nop 0
	v_pk_add_f32 v[50:51], v[50:51], 1.0 op_sel_hi:[1,0]
	s_nop 0
	v_pk_mul_f32 v[48:49], v[48:49], v[50:51]
	s_nop 0
	v_cvt_pk_bf16_f32 v47, v48, v49
	global_store_dwordx2 v[42:43], v[46:47], off offset:-4
	v_lshl_add_u64 v[42:43], v[42:43], 0, s[14:15]
.Ls5p_end:
	s_waitcnt lgkmcnt(0)
	s_barrier
.LBB0_444:
	s_and_saveexec_b64 s[0:1], s[10:11]
	s_xor_b64 s[0:1], exec, s[0:1]
	s_cbranch_execz .LBB0_189
	s_ashr_i32 s37, s36, 31
	v_lshlrev_b64 v[2:3], 2, v[162:163]
	s_lshl_b64 s[14:15], s[36:37], 8
	v_or_b32_e32 v3, s15, v3
	v_or_b32_e32 v2, s14, v2
	v_readlane_b32 s12, v251, 40
	v_readlane_b32 s22, v251, 50
	v_readlane_b32 s23, v251, 51
	v_readlane_b32 s24, v251, 52
	v_readlane_b32 s25, v251, 53
	s_mov_b32 s37, 0x7f800000
	v_readlane_b32 s13, v251, 41
	v_lshl_add_u64 v[8:9], s[24:25], 0, v[2:3]
	v_lshl_add_u64 v[2:3], s[22:23], 0, v[2:3]
	v_readlane_b32 s14, v251, 42
	v_readlane_b32 s15, v251, 43
	v_readlane_b32 s16, v251, 44
	v_readlane_b32 s17, v251, 45
	v_readlane_b32 s18, v251, 46
	v_readlane_b32 s19, v251, 47
	v_readlane_b32 s20, v251, 48
	v_readlane_b32 s21, v251, 49
	v_readlane_b32 s26, v251, 54
	v_readlane_b32 s27, v251, 55
	global_store_dword v[2:3], v44, off
	global_store_dword v[8:9], v45, off
	s_branch .LBB0_189
